# stack of all edits: hazard-pad replacement + in-proj loop-edge rotation + static priority in the RG-LRU loops
# baseline (speedup 1.0000x reference)
; #define PG8_STAGE(bufoff, gbase, voff) do { _Pragma("unroll") for (int _i = 0; _i < 2; ++_i) \
;         __builtin_amdgcn_global_load_lds((const unsigned*)((const char*)(gbase) + (voff)[_i]), (LAS unsigned*)(lds + (bufoff) + ldsw + _i * 8192), 16, 0, 0); } while (0)
; #define PG8_LDA(dst, b, h) do { _Pragma("unroll") for (int m = 0; m < 4; ++m) _Pragma("unroll") for (int k = 0; k < 2; ++k) dst[m][k] = *(const LAS bf16x8*)(lds + PG8_SA(b, h) + aoff + m * 2048 + k * 1024); } while (0)
; #define PG8_LDB(dst, b, h) do { _Pragma("unroll") for (int n = 0; n < 2; ++n) _Pragma("unroll") for (int k = 0; k < 2; ++k) dst[n][k] = *(const LAS bf16x8*)(lds + PG8_SB(b, h) + boff + n * 2048 + k * 1024); } while (0)
; #define PG8_MMA(ai, bj, At, Bt) do { __builtin_amdgcn_s_setprio(1); _Pragma("unroll") for (int m = 0; m < 4; ++m) _Pragma("unroll") for (int n = 0; n < 2; ++n) _Pragma("unroll") for (int k = 0; k < 2; ++k) \
;         acc[ai][bj][m][n] = __builtin_amdgcn_mfma_f32_16x16x32_bf16(Bt[n][k], At[m][k], acc[ai][bj][m][n], 0, 0, 0); __builtin_amdgcn_s_setprio(0); } while (0)
; #define PG8_WAIT_V(n) asm volatile("s_waitcnt vmcnt(" #n ")" ::: "memory")
; #define PG8_WAIT_L(n) asm volatile("s_waitcnt lgkmcnt(" #n ")" ::: "memory")
; #define PG8_BAR __builtin_amdgcn_s_barrier()
; #define PG8_SCHED __builtin_amdgcn_sched_barrier(0)
; template <class Epi, class Sched>
; __device__ __forceinline__ void gemm_phase(const int TID, LAS unsigned char* lds, const int lda, const int ldb, const Sched& S, const Epi& E) {
;     ...
;             PG8_LDB(B0, 0, 0); PG8_SCHED; PG8_LDA(At, 0, 0); PG8_STAGE(PG8_SA(1, 1), a1 + hA, voffA);
;             PG8_WAIT_L(8); PG8_BAR; PG8_WAIT_L(0); PG8_MMA(0, 0, At, B0); PG8_BAR; PG8_SCHED;
;             PG8_LDB(B1, 0, 1); PG8_STAGE(PG8_SB(0, 0), b2, voffB);
;             PG8_BAR; PG8_WAIT_L(0); PG8_MMA(0, 1, At, B1); PG8_BAR;
;             PG8_LDA(At, 0, 1); PG8_STAGE(PG8_SA(0, 0), a2, voffA);
;             PG8_BAR; PG8_WAIT_L(0); PG8_MMA(1, 0, At, B0); PG8_BAR; PG8_SCHED;
;             PG8_STAGE(PG8_SB(0, 1), b2 + hB, voffB);
;             PG8_WAIT_V(6); PG8_BAR; PG8_MMA(1, 1, At, B1); PG8_BAR;
.Lk1_body:
	ds_read_b128 v[170:173], v157
	ds_read_b128 v[174:177], v157 offset:1024
	ds_read_b128 v[178:181], v157 offset:2048
	ds_read_b128 v[196:199], v157 offset:3072
	ds_read_b128 v[200:203], v157 offset:4096
	ds_read_b128 v[204:207], v157 offset:5120
	ds_read_b128 v[208:211], v157 offset:6144
	ds_read_b128 v[212:215], v157 offset:7168
	global_load_lds_dwordx4 v[154:155], off
	s_add_i32 m0, s57, 0xe000
	v_lshl_add_u64 v[154:155], s[46:47], 0, v[146:147]
	global_load_lds_dwordx4 v[154:155], off
	s_waitcnt lgkmcnt(8)
	s_barrier
	s_waitcnt lgkmcnt(0)
	s_waitcnt lgkmcnt(0)
	v_mfma_f32_16x16x32_bf16 v[130:133], v[150:153], v[170:173], v[130:133]
	v_mfma_f32_16x16x32_bf16 v[126:129], v[162:165], v[170:173], v[126:129]
	v_mfma_f32_16x16x32_bf16 v[114:117], v[150:153], v[178:181], v[114:117]
	v_mfma_f32_16x16x32_bf16 v[110:113], v[162:165], v[178:181], v[110:113]
	v_mfma_f32_16x16x32_bf16 v[98:101], v[150:153], v[200:203], v[98:101]
	v_mfma_f32_16x16x32_bf16 v[94:97], v[162:165], v[200:203], v[94:97]
	v_mfma_f32_16x16x32_bf16 v[82:85], v[150:153], v[208:211], v[82:85]
	v_mfma_f32_16x16x32_bf16 v[78:81], v[162:165], v[208:211], v[78:81]
	v_mfma_f32_16x16x32_bf16 v[130:133], v[158:161], v[174:177], v[130:133]
	v_mfma_f32_16x16x32_bf16 v[126:129], v[166:169], v[174:177], v[126:129]
	v_mfma_f32_16x16x32_bf16 v[114:117], v[158:161], v[196:199], v[114:117]
	v_mfma_f32_16x16x32_bf16 v[110:113], v[166:169], v[196:199], v[110:113]
	v_mfma_f32_16x16x32_bf16 v[98:101], v[158:161], v[204:207], v[98:101]
	v_mfma_f32_16x16x32_bf16 v[94:97], v[166:169], v[204:207], v[94:97]
	v_mfma_f32_16x16x32_bf16 v[82:85], v[158:161], v[212:215], v[82:85]
	v_mfma_f32_16x16x32_bf16 v[78:81], v[166:169], v[212:215], v[78:81]
	s_barrier
	s_add_i32 s8, 0, 0x14000
	v_add_u32_e32 v154, s8, v13
	s_add_i32 s9, s10, s56
	ds_read_b128 v[216:219], v154
	ds_read_b128 v[220:223], v154 offset:1024
	ds_read_b128 v[236:239], v154 offset:2048
	ds_read_b128 v[240:243], v154 offset:3072
	v_lshl_add_u64 v[154:155], s[48:49], 0, v[136:137]
	s_mov_b32 m0, s9
	v_lshl_add_u64 v[186:187], s[48:49], 0, v[140:141]
	global_load_lds_dwordx4 v[154:155], off
	s_add_i32 m0, s9, 0x2000
	s_nop 0
	global_load_lds_dwordx4 v[186:187], off
	s_barrier
	s_waitcnt lgkmcnt(0)
	s_waitcnt lgkmcnt(0)
	v_mfma_f32_16x16x32_bf16 v[122:125], v[216:219], v[170:173], v[122:125]
	v_mfma_f32_16x16x32_bf16 v[118:121], v[236:239], v[170:173], v[118:121]
	v_mfma_f32_16x16x32_bf16 v[106:109], v[216:219], v[178:181], v[106:109]
	v_mfma_f32_16x16x32_bf16 v[102:105], v[236:239], v[178:181], v[102:105]
	v_mfma_f32_16x16x32_bf16 v[90:93], v[216:219], v[200:203], v[90:93]
	v_mfma_f32_16x16x32_bf16 v[86:89], v[236:239], v[200:203], v[86:89]
	v_mfma_f32_16x16x32_bf16 v[74:77], v[216:219], v[208:211], v[74:77]
	v_mfma_f32_16x16x32_bf16 v[70:73], v[236:239], v[208:211], v[70:73]
	v_mfma_f32_16x16x32_bf16 v[122:125], v[220:223], v[174:177], v[122:125]
	v_mfma_f32_16x16x32_bf16 v[118:121], v[240:243], v[174:177], v[118:121]
	v_mfma_f32_16x16x32_bf16 v[106:109], v[220:223], v[196:199], v[106:109]
	v_mfma_f32_16x16x32_bf16 v[102:105], v[240:243], v[196:199], v[102:105]
	v_mfma_f32_16x16x32_bf16 v[90:93], v[220:223], v[204:207], v[90:93]
	v_mfma_f32_16x16x32_bf16 v[86:89], v[240:243], v[204:207], v[86:89]
	v_mfma_f32_16x16x32_bf16 v[74:77], v[220:223], v[212:215], v[74:77]
	v_mfma_f32_16x16x32_bf16 v[70:73], v[240:243], v[212:215], v[70:73]
	s_mov_b32 m0, s57
	v_lshl_add_u64 v[188:189], s[50:51], 0, v[134:135]
	s_barrier
	ds_read_b128 v[170:173], v157 offset:16384
	ds_read_b128 v[174:177], v157 offset:17408
	ds_read_b128 v[178:181], v157 offset:18432
	ds_read_b128 v[196:199], v157 offset:19456
	ds_read_b128 v[200:203], v157 offset:20480
	ds_read_b128 v[204:207], v157 offset:21504
	ds_read_b128 v[208:211], v157 offset:22528
	ds_read_b128 v[212:215], v157 offset:23552
	global_load_lds_dwordx4 v[188:189], off
	s_mov_b32 m0, s58
	v_lshl_add_u64 v[244:245], s[50:51], 0, v[138:139]
	global_load_lds_dwordx4 v[244:245], off
	s_barrier
	s_waitcnt lgkmcnt(0)
	s_waitcnt lgkmcnt(0)
	v_mfma_f32_16x16x32_bf16 v[66:69], v[150:153], v[170:173], v[66:69]
	v_mfma_f32_16x16x32_bf16 v[62:65], v[162:165], v[170:173], v[62:65]
	v_mfma_f32_16x16x32_bf16 v[50:53], v[150:153], v[178:181], v[50:53]
	v_mfma_f32_16x16x32_bf16 v[46:49], v[162:165], v[178:181], v[46:49]
	v_mfma_f32_16x16x32_bf16 v[34:37], v[150:153], v[200:203], v[34:37]
	v_mfma_f32_16x16x32_bf16 v[30:33], v[162:165], v[200:203], v[30:33]
	v_mfma_f32_16x16x32_bf16 v[18:21], v[150:153], v[208:211], v[18:21]
	v_mfma_f32_16x16x32_bf16 v[8:11], v[162:165], v[208:211], v[8:11]
	v_mfma_f32_16x16x32_bf16 v[66:69], v[158:161], v[174:177], v[66:69]
	v_mfma_f32_16x16x32_bf16 v[62:65], v[166:169], v[174:177], v[62:65]
	v_mfma_f32_16x16x32_bf16 v[50:53], v[158:161], v[196:199], v[50:53]
	v_mfma_f32_16x16x32_bf16 v[46:49], v[166:169], v[196:199], v[46:49]
	v_mfma_f32_16x16x32_bf16 v[34:37], v[158:161], v[204:207], v[34:37]
	v_mfma_f32_16x16x32_bf16 v[30:33], v[166:169], v[204:207], v[30:33]
	v_mfma_f32_16x16x32_bf16 v[18:21], v[158:161], v[212:215], v[18:21]
	v_mfma_f32_16x16x32_bf16 v[8:11], v[166:169], v[212:215], v[8:11]
	s_barrier
	s_add_u32 s66, s48, 0x80000
	s_addc_u32 s67, s49, 0
	s_add_i32 s8, s8, s56
	s_mov_b32 m0, s8
	v_lshl_add_u64 v[150:151], s[66:67], 0, v[136:137]
	global_load_lds_dwordx4 v[150:151], off
	s_add_i32 m0, s8, 0x2000
	v_lshl_add_u64 v[150:151], s[66:67], 0, v[140:141]
	global_load_lds_dwordx4 v[150:151], off
	s_waitcnt vmcnt(6)
	s_barrier
; #define PG8_STAGE(bufoff, gbase, voff) do { _Pragma("unroll") for (int _i = 0; _i < 2; ++_i) \
;         __builtin_amdgcn_global_load_lds((const unsigned*)((const char*)(gbase) + (voff)[_i]), (LAS unsigned*)(lds + (bufoff) + ldsw + _i * 8192), 16, 0, 0); } while (0)
; #define PG8_LDA(dst, b, h) do { _Pragma("unroll") for (int m = 0; m < 4; ++m) _Pragma("unroll") for (int k = 0; k < 2; ++k) dst[m][k] = *(const LAS bf16x8*)(lds + PG8_SA(b, h) + aoff + m * 2048 + k * 1024); } while (0)
; #define PG8_LDB(dst, b, h) do { _Pragma("unroll") for (int n = 0; n < 2; ++n) _Pragma("unroll") for (int k = 0; k < 2; ++k) dst[n][k] = *(const LAS bf16x8*)(lds + PG8_SB(b, h) + boff + n * 2048 + k * 1024); } while (0)
; #define PG8_MMA(ai, bj, At, Bt) do { __builtin_amdgcn_s_setprio(1); _Pragma("unroll") for (int m = 0; m < 4; ++m) _Pragma("unroll") for (int n = 0; n < 2; ++n) _Pragma("unroll") for (int k = 0; k < 2; ++k) \
;         acc[ai][bj][m][n] = __builtin_amdgcn_mfma_f32_16x16x32_bf16(Bt[n][k], At[m][k], acc[ai][bj][m][n], 0, 0, 0); __builtin_amdgcn_s_setprio(0); } while (0)
; #define PG8_WAIT_V(n) asm volatile("s_waitcnt vmcnt(" #n ")" ::: "memory")
; #define PG8_WAIT_L(n) asm volatile("s_waitcnt lgkmcnt(" #n ")" ::: "memory")
; #define PG8_BAR __builtin_amdgcn_s_barrier()
; #define PG8_SCHED __builtin_amdgcn_sched_barrier(0)
; template <class Epi, class Sched>
; __device__ __forceinline__ void gemm_phase(const int TID, LAS unsigned char* lds, const int lda, const int ldb, const Sched& S, const Epi& E) {
;     ...
;             PG8_WAIT_V(6); PG8_BAR; PG8_MMA(1, 1, At, B1); PG8_BAR;
;             PG8_LDB(B0, 1, 0); PG8_SCHED; PG8_LDA(At, 1, 0); PG8_STAGE(PG8_SA(0, 1), a2 + hA, voffA);
;             PG8_WAIT_L(8); PG8_BAR; PG8_WAIT_L(0); PG8_MMA(0, 0, At, B0); PG8_BAR; PG8_SCHED;
;             PG8_LDB(B1, 1, 1); PG8_STAGE(PG8_SB(1, 0), b3, voffB);
;             PG8_BAR; PG8_WAIT_L(0); PG8_MMA(0, 1, At, B1); PG8_BAR;
;             PG8_LDA(At, 1, 1); PG8_STAGE(PG8_SA(1, 0), a3, voffA);
;             PG8_BAR; PG8_WAIT_L(0); PG8_MMA(1, 0, At, B0); PG8_BAR; PG8_SCHED;
	v_add_u32_e32 v166, 0x18000, v13
	v_mfma_f32_16x16x32_bf16 v[58:61], v[216:219], v[170:173], v[58:61]
	v_mfma_f32_16x16x32_bf16 v[54:57], v[236:239], v[170:173], v[54:57]
	v_mfma_f32_16x16x32_bf16 v[42:45], v[216:219], v[178:181], v[42:45]
	v_mfma_f32_16x16x32_bf16 v[38:41], v[236:239], v[178:181], v[38:41]
	ds_read_b128 v[150:153], v166
	v_mfma_f32_16x16x32_bf16 v[26:29], v[216:219], v[200:203], v[26:29]
	v_mfma_f32_16x16x32_bf16 v[22:25], v[236:239], v[200:203], v[22:25]
	ds_read_b128 v[158:161], v166 offset:1024
	v_mfma_f32_16x16x32_bf16 v[4:7], v[216:219], v[208:211], v[4:7]
	v_mfma_f32_16x16x32_bf16 v[0:3], v[236:239], v[208:211], v[0:3]
	ds_read_b128 v[162:165], v166 offset:2048
	v_mfma_f32_16x16x32_bf16 v[58:61], v[220:223], v[174:177], v[58:61]
	v_mfma_f32_16x16x32_bf16 v[54:57], v[240:243], v[174:177], v[54:57]
	ds_read_b128 v[166:169], v166 offset:3072
	v_mfma_f32_16x16x32_bf16 v[42:45], v[220:223], v[196:199], v[42:45]
	v_mfma_f32_16x16x32_bf16 v[38:41], v[240:243], v[196:199], v[38:41]
	v_mfma_f32_16x16x32_bf16 v[26:29], v[220:223], v[204:207], v[26:29]
	v_mfma_f32_16x16x32_bf16 v[22:25], v[240:243], v[204:207], v[22:25]
	v_mfma_f32_16x16x32_bf16 v[4:7], v[220:223], v[212:215], v[4:7]
	v_mfma_f32_16x16x32_bf16 v[0:3], v[240:243], v[212:215], v[0:3]
	s_add_i32 s8, 0, 0x18000
	s_barrier
	s_add_u32 s50, s50, 0x80000
	s_addc_u32 s51, s51, 0
	s_mov_b32 m0, s59
	v_lshl_add_u64 v[216:217], s[50:51], 0, v[134:135]
	ds_read_b128 v[170:173], v157 offset:32768
	ds_read_b128 v[174:177], v157 offset:33792
	ds_read_b128 v[178:181], v157 offset:34816
	ds_read_b128 v[196:199], v157 offset:35840
	ds_read_b128 v[200:203], v157 offset:36864
	ds_read_b128 v[204:207], v157 offset:37888
	ds_read_b128 v[208:211], v157 offset:38912
	ds_read_b128 v[212:215], v157 offset:39936
	global_load_lds_dwordx4 v[216:217], off
	s_mov_b32 m0, s60
	v_lshl_add_u64 v[216:217], s[50:51], 0, v[138:139]
	global_load_lds_dwordx4 v[216:217], off
	s_waitcnt lgkmcnt(8)
	s_barrier
	s_waitcnt lgkmcnt(0)
	s_waitcnt lgkmcnt(0)
	v_mfma_f32_16x16x32_bf16 v[130:133], v[150:153], v[170:173], v[130:133]
	v_mfma_f32_16x16x32_bf16 v[126:129], v[162:165], v[170:173], v[126:129]
	v_mfma_f32_16x16x32_bf16 v[114:117], v[150:153], v[178:181], v[114:117]
	v_mfma_f32_16x16x32_bf16 v[110:113], v[162:165], v[178:181], v[110:113]
	v_mfma_f32_16x16x32_bf16 v[98:101], v[150:153], v[200:203], v[98:101]
	v_mfma_f32_16x16x32_bf16 v[94:97], v[162:165], v[200:203], v[94:97]
	v_mfma_f32_16x16x32_bf16 v[82:85], v[150:153], v[208:211], v[82:85]
	v_mfma_f32_16x16x32_bf16 v[78:81], v[162:165], v[208:211], v[78:81]
	v_mfma_f32_16x16x32_bf16 v[130:133], v[158:161], v[174:177], v[130:133]
	v_mfma_f32_16x16x32_bf16 v[126:129], v[166:169], v[174:177], v[126:129]
	v_mfma_f32_16x16x32_bf16 v[114:117], v[158:161], v[196:199], v[114:117]
	v_mfma_f32_16x16x32_bf16 v[110:113], v[166:169], v[196:199], v[110:113]
	v_mfma_f32_16x16x32_bf16 v[98:101], v[158:161], v[204:207], v[98:101]
	v_mfma_f32_16x16x32_bf16 v[94:97], v[166:169], v[204:207], v[94:97]
	v_mfma_f32_16x16x32_bf16 v[82:85], v[158:161], v[212:215], v[82:85]
	v_mfma_f32_16x16x32_bf16 v[78:81], v[166:169], v[212:215], v[78:81]
	s_barrier
	s_add_i32 s9, 0, 0x1c000
	s_add_i32 s8, s8, s56
	v_add_u32_e32 v182, s9, v13
	v_lshl_add_u64 v[154:155], v[154:155], 0, s[36:37]
	s_mov_b32 m0, s8
	ds_read_b128 v[216:219], v182
	ds_read_b128 v[220:223], v182 offset:1024
	ds_read_b128 v[236:239], v182 offset:2048
	ds_read_b128 v[240:243], v182 offset:3072
	global_load_lds_dwordx4 v[154:155], off
	s_add_i32 m0, s8, 0x2000
	v_lshl_add_u64 v[154:155], v[186:187], 0, s[36:37]
	global_load_lds_dwordx4 v[154:155], off
	s_barrier
	s_waitcnt lgkmcnt(0)
	s_waitcnt lgkmcnt(0)
	v_mfma_f32_16x16x32_bf16 v[122:125], v[216:219], v[170:173], v[122:125]
	v_mfma_f32_16x16x32_bf16 v[118:121], v[236:239], v[170:173], v[118:121]
	v_mfma_f32_16x16x32_bf16 v[106:109], v[216:219], v[178:181], v[106:109]
	v_mfma_f32_16x16x32_bf16 v[102:105], v[236:239], v[178:181], v[102:105]
	v_mfma_f32_16x16x32_bf16 v[90:93], v[216:219], v[200:203], v[90:93]
	v_mfma_f32_16x16x32_bf16 v[86:89], v[236:239], v[200:203], v[86:89]
	v_mfma_f32_16x16x32_bf16 v[74:77], v[216:219], v[208:211], v[74:77]
	v_mfma_f32_16x16x32_bf16 v[70:73], v[236:239], v[208:211], v[70:73]
	v_mfma_f32_16x16x32_bf16 v[122:125], v[220:223], v[174:177], v[122:125]
	v_mfma_f32_16x16x32_bf16 v[118:121], v[240:243], v[174:177], v[118:121]
	v_mfma_f32_16x16x32_bf16 v[106:109], v[220:223], v[196:199], v[106:109]
	v_mfma_f32_16x16x32_bf16 v[102:105], v[240:243], v[196:199], v[102:105]
	v_mfma_f32_16x16x32_bf16 v[90:93], v[220:223], v[204:207], v[90:93]
	v_mfma_f32_16x16x32_bf16 v[86:89], v[240:243], v[204:207], v[86:89]
	v_mfma_f32_16x16x32_bf16 v[74:77], v[220:223], v[212:215], v[74:77]
	v_mfma_f32_16x16x32_bf16 v[70:73], v[240:243], v[212:215], v[70:73]
	s_mov_b32 m0, s62
	v_lshl_add_u64 v[154:155], v[188:189], 0, s[36:37]
	s_barrier
; #define PG8_STAGE(bufoff, gbase, voff) do { _Pragma("unroll") for (int _i = 0; _i < 2; ++_i) \
;         __builtin_amdgcn_global_load_lds((const unsigned*)((const char*)(gbase) + (voff)[_i]), (LAS unsigned*)(lds + (bufoff) + ldsw + _i * 8192), 16, 0, 0); } while (0)
; #define PG8_WAIT_V(n) asm volatile("s_waitcnt vmcnt(" #n ")" ::: "memory")
; #define PG8_WAIT_L(n) asm volatile("s_waitcnt lgkmcnt(" #n ")" ::: "memory")
; template <class Epi, class Sched>
; __device__ __forceinline__ void gemm_phase(const int TID, LAS unsigned char* lds, const int lda, const int ldb, const Sched& S, const Epi& E) {
;     ...
;         const bool has_next = S.next(ui + 1, nxt);
;         const char* nA = has_next ? nxt.a : cA; const char* nB = has_next ? nxt.b : cB;
;         const int nt = cur.nt;
;         for (int t = 0; t < nt; t += 2) {
;             const bool last = (t == nt - 2);
;             const char* a1 = cA + (size_t)(t + 1) * kstep;
;             const char* a2 = last ? nA : cA + (size_t)(t + 2) * kstep; const char* b2 = last ? nB : cB + (size_t)(t + 2) * kstep;
;             const char* a3 = a2 + kstep; const char* b3 = b2 + kstep;
;             PG8_LDB(B0, 0, 0); PG8_SCHED; PG8_LDA(At, 0, 0); PG8_STAGE(PG8_SA(1, 1), a1 + hA, voffA);
;             PG8_WAIT_L(8); PG8_BAR; PG8_WAIT_L(0); PG8_MMA(0, 0, At, B0); PG8_BAR; PG8_SCHED;
;             PG8_LDB(B1, 0, 1); PG8_STAGE(PG8_SB(0, 0), b2, voffB);
;             PG8_BAR; PG8_WAIT_L(0); PG8_MMA(0, 1, At, B1); PG8_BAR;
;             PG8_LDA(At, 0, 1); PG8_STAGE(PG8_SA(0, 0), a2, voffA);
;             PG8_BAR; PG8_WAIT_L(0); PG8_MMA(1, 0, At, B0); PG8_BAR; PG8_SCHED;
;             PG8_STAGE(PG8_SB(0, 1), b2 + hB, voffB);
;             PG8_WAIT_V(6); PG8_BAR; PG8_MMA(1, 1, At, B1); PG8_BAR;
;             PG8_LDB(B0, 1, 0); PG8_SCHED; PG8_LDA(At, 1, 0); PG8_STAGE(PG8_SA(0, 1), a2 + hA, voffA);
;             PG8_WAIT_L(8); PG8_BAR; PG8_WAIT_L(0); PG8_MMA(0, 0, At, B0); PG8_BAR; PG8_SCHED;
;             PG8_LDB(B1, 1, 1); PG8_STAGE(PG8_SB(1, 0), b3, voffB);
;             PG8_BAR; PG8_WAIT_L(0); PG8_MMA(0, 1, At, B1); PG8_BAR;
;             PG8_LDA(At, 1, 1); PG8_STAGE(PG8_SA(1, 0), a3, voffA);
;             PG8_BAR; PG8_WAIT_L(0); PG8_MMA(1, 0, At, B0); PG8_BAR; PG8_SCHED;
;             PG8_STAGE(PG8_SB(1, 1), b3 + hB, voffB);
;             PG8_WAIT_V(6); PG8_BAR; PG8_MMA(1, 1, At, B1); PG8_BAR;
;         }
	ds_read_b128 v[170:173], v157 offset:49152
	ds_read_b128 v[174:177], v157 offset:50176
	ds_read_b128 v[178:181], v157 offset:51200
	ds_read_b128 v[196:199], v157 offset:52224
	ds_read_b128 v[200:203], v157 offset:53248
	ds_read_b128 v[204:207], v157 offset:54272
	ds_read_b128 v[208:211], v157 offset:55296
	ds_read_b128 v[212:215], v157 offset:56320
	global_load_lds_dwordx4 v[154:155], off
	s_mov_b32 m0, s63
	v_lshl_add_u64 v[154:155], v[244:245], 0, s[36:37]
	global_load_lds_dwordx4 v[154:155], off
	s_barrier
	s_waitcnt lgkmcnt(0)
	s_waitcnt lgkmcnt(0)
	v_mfma_f32_16x16x32_bf16 v[66:69], v[150:153], v[170:173], v[66:69]
	v_mfma_f32_16x16x32_bf16 v[62:65], v[162:165], v[170:173], v[62:65]
	v_mfma_f32_16x16x32_bf16 v[50:53], v[150:153], v[178:181], v[50:53]
	v_mfma_f32_16x16x32_bf16 v[46:49], v[162:165], v[178:181], v[46:49]
	v_mfma_f32_16x16x32_bf16 v[34:37], v[150:153], v[200:203], v[34:37]
	v_mfma_f32_16x16x32_bf16 v[30:33], v[162:165], v[200:203], v[30:33]
	v_mfma_f32_16x16x32_bf16 v[18:21], v[150:153], v[208:211], v[18:21]
	v_mfma_f32_16x16x32_bf16 v[8:11], v[162:165], v[208:211], v[8:11]
	v_mfma_f32_16x16x32_bf16 v[66:69], v[158:161], v[174:177], v[66:69]
	v_mfma_f32_16x16x32_bf16 v[62:65], v[166:169], v[174:177], v[62:65]
	v_mfma_f32_16x16x32_bf16 v[50:53], v[158:161], v[196:199], v[50:53]
	v_mfma_f32_16x16x32_bf16 v[46:49], v[166:169], v[196:199], v[46:49]
	v_mfma_f32_16x16x32_bf16 v[34:37], v[158:161], v[204:207], v[34:37]
	v_mfma_f32_16x16x32_bf16 v[30:33], v[166:169], v[204:207], v[30:33]
	v_mfma_f32_16x16x32_bf16 v[18:21], v[158:161], v[212:215], v[18:21]
	v_mfma_f32_16x16x32_bf16 v[8:11], v[166:169], v[212:215], v[8:11]
	s_barrier
	s_add_u32 s48, s48, 0x80080
	s_addc_u32 s49, s49, 0
	s_add_i32 s8, s9, s56
	s_mov_b32 m0, s8
	v_lshl_add_u64 v[150:151], s[48:49], 0, v[136:137]
	global_load_lds_dwordx4 v[150:151], off
	s_add_i32 m0, s8, 0x2000
	v_lshl_add_u64 v[150:151], s[48:49], 0, v[140:141]
	global_load_lds_dwordx4 v[150:151], off
	s_waitcnt vmcnt(6)
	s_barrier
	v_add_u32_e32 v154, 0x10000, v13
	v_mfma_f32_16x16x32_bf16 v[58:61], v[216:219], v[170:173], v[58:61]
	v_mfma_f32_16x16x32_bf16 v[54:57], v[236:239], v[170:173], v[54:57]
	v_mfma_f32_16x16x32_bf16 v[42:45], v[216:219], v[178:181], v[42:45]
	v_mfma_f32_16x16x32_bf16 v[38:41], v[236:239], v[178:181], v[38:41]
	ds_read_b128 v[150:153], v154
	v_mfma_f32_16x16x32_bf16 v[26:29], v[216:219], v[200:203], v[26:29]
	v_mfma_f32_16x16x32_bf16 v[22:25], v[236:239], v[200:203], v[22:25]
	ds_read_b128 v[158:161], v154 offset:1024
	v_mfma_f32_16x16x32_bf16 v[4:7], v[216:219], v[208:211], v[4:7]
	v_mfma_f32_16x16x32_bf16 v[0:3], v[236:239], v[208:211], v[0:3]
	ds_read_b128 v[162:165], v154 offset:2048
	v_mfma_f32_16x16x32_bf16 v[58:61], v[220:223], v[174:177], v[58:61]
	v_mfma_f32_16x16x32_bf16 v[54:57], v[240:243], v[174:177], v[54:57]
	ds_read_b128 v[166:169], v154 offset:3072
	v_mfma_f32_16x16x32_bf16 v[42:45], v[220:223], v[196:199], v[42:45]
	v_mfma_f32_16x16x32_bf16 v[38:41], v[240:243], v[196:199], v[38:41]
	v_mfma_f32_16x16x32_bf16 v[26:29], v[220:223], v[204:207], v[26:29]
	v_mfma_f32_16x16x32_bf16 v[22:25], v[240:243], v[204:207], v[22:25]
	v_mfma_f32_16x16x32_bf16 v[4:7], v[220:223], v[212:215], v[4:7]
	v_mfma_f32_16x16x32_bf16 v[0:3], v[240:243], v[212:215], v[0:3]
	s_add_i32 s29, s29, 2
	s_add_u32 s3, s3, 0x100
	s_addc_u32 s24, s24, 0
	s_add_u32 s46, s46, 0x100
	s_addc_u32 s47, s47, 0
	s_add_u32 s8, s46, 0xfff80080
	s_addc_u32 s9, s47, -1
	s_add_i32 s10, 0, 0x10000
	s_cmp_eq_u32 s29, 28
	s_cselect_b32 s51, s43, s9
	s_cselect_b32 s50, s42, s8
	s_cselect_b32 s49, s45, s24
	s_cselect_b32 s48, s44, s3
	v_lshl_add_u64 v[154:155], s[46:47], 0, v[148:149]
	s_add_i32 m0, s57, 0xc000
	s_cmp_gt_u32 s29, 29
	s_barrier
	s_cbranch_scc0 .Lk1_body
	s_setprio 0
	s_waitcnt lgkmcnt(0)
	s_lshl_b32 s3, s40, 8
	s_sub_i32 s8, s65, 18
	s_add_i32 s3, s3, s61
	s_lshl_b32 s24, s65, 8
	s_cmp_gt_u32 s8, 23
	v_or_b32_e32 v158, s3, v12
	s_mov_b64 s[40:41], -1
	s_cbranch_scc0 .LBB0_1295
	s_cmp_gt_i32 s65, 1
	s_cselect_b64 s[46:47], -1, 0
	v_mad_i64_i32 v[150:151], s[40:41], v158, s4, 0
	v_or_b32_e32 v182, s24, v156
	s_mov_b64 s[40:41], -1
	s_and_b64 vcc, exec, s[46:47]
	v_lshl_add_u64 v[150:151], s[0:1], 0, v[150:151]
	s_cbranch_vccz .LBB0_1232
	v_lshl_add_u64 v[152:153], v[182:183], 1, v[150:151]
	s_mov_b64 s[40:41], 0
